# GU/D2/OUT seams: 4-workgroup row-panel group barriers (direct poll)
# baseline (speedup 1.0000x reference)
; __device__ __forceinline__ unsigned xb_ld(unsigned* p)              { return __hip_atomic_load(p, __ATOMIC_RELAXED, __HIP_MEMORY_SCOPE_AGENT); }
; __device__ __forceinline__ unsigned xb_add(unsigned* p, unsigned v) { return __hip_atomic_fetch_add(p, v, __ATOMIC_RELAXED, __HIP_MEMORY_SCOPE_AGENT); }
; #define XB_SPIN(cond, bar) do { unsigned _sp = 0; while (cond) { __builtin_amdgcn_s_sleep(8); \
;     if ((++_sp & 255u) == 0u) { if (xb_ld(&(bar)[XB_TMO])) break; if (_sp > XB_SPIN_CAP) { atomicAdd(&(bar)[XB_TMO], 1u); break; } } } } while (0)
; __device__ __forceinline__ void xcd_barrier(const XcdBarrier& b) {
;     asm volatile("s_waitcnt vmcnt(0)" ::: "memory");
;     __syncthreads();
;     if (threadIdx.x == 0) {
;         unsigned* bar = b.bar;
;         __builtin_amdgcn_s_waitcnt(0);
;         unsigned nloc = b.st[0], nx = b.st[1];
;         if (nloc == 0u) { xcd_barrier_complete(bar, b.x, nloc, nx); b.st[0] = nloc; b.st[1] = nx; }
;         const unsigned old = xb_add(&bar[XB_XSUB(b.x)], 1u);
;         const unsigned gen = old / nloc;
;         if (old + 1u == (gen + 1u) * nloc) {
;             __builtin_amdgcn_fence(__ATOMIC_RELEASE, "agent");
;             asm volatile("s_waitcnt vmcnt(0)" ::: "memory");
;             const unsigned og = xb_add(&bar[XB_TOP], 1u);
;             const unsigned tg = og / nx;
;             if (og + 1u == (tg + 1u) * nx) xb_add(&bar[XB_TOPGEN], 1u);
;             else XB_SPIN(xb_ld(&bar[XB_TOPGEN]) == tg, bar);
;             __builtin_amdgcn_fence(__ATOMIC_ACQUIRE, "agent");
;             xb_add(&bar[XB_XGEN(b.x)], 1u);
;             asm volatile("s_waitcnt vmcnt(0)" ::: "memory");
;         } else {
;             XB_SPIN(xb_ld(&bar[XB_XGEN(b.x)]) == gen, bar);
;             __builtin_amdgcn_fence(__ATOMIC_ACQUIRE, "agent");
;             asm volatile("s_waitcnt vmcnt(0)" ::: "memory");
;         }
;     }
;     __syncthreads();
; }
.LBB0_404:
	v_readlane_b32 s6, v252, 34
	v_readlane_b32 s7, v252, 35
	v_mov_b32_e32 v15, 0x23080
	v_mov_b32_e32 v17, 0x80
	ds_add_rtn_u32 v17, v15, v17
	s_nop 2
	global_load_dword v16, v1, s[6:7] offset:-256 sc1
	v_mov_b32_e32 v14, 0x23084
	ds_read_b32 v14, v14
	s_waitcnt lgkmcnt(0)
	v_readfirstlane_b32 s9, v14
	s_nop 3
	s_cmp_eq_u32 s9, 0
	s_cbranch_scc1 .Lgu_full
	v_readlane_b32 s8, v252, 34
	v_readlane_b32 s9, v252, 35
	s_and_b32 s30, s2, 7
	s_lshl_b32 s30, s30, 3
	s_bfe_u32 s31, s2, 0x30003
	s_or_b32 s30, s30, s31
	s_lshl_b32 s30, s30, 5
	s_addk_i32 s30, 0x3600
	s_add_u32 s8, s8, s30
	s_addc_u32 s9, s9, 0
	v_mov_b32_e32 v14, 0x23088
	v_mov_b32_e32 v12, 4
	ds_add_rtn_u32 v13, v14, v12
	v_mov_b32_e32 v11, 1
	s_nop 1
	global_atomic_add v1, v11, s[8:9]
	s_waitcnt lgkmcnt(0)
	v_add_u32_e32 v13, 4, v13
	v_add_u32_e32 v17, 0x80, v17
	s_mov_b32 s5, 0
.Lgu_lpoll:
	global_load_dword v12, v1, s[8:9] sc1
	s_waitcnt vmcnt(0)
	v_cmp_ge_u32_e32 vcc, v12, v13
	v_cmp_ge_u32_e64 s[30:31], v16, v17
	s_nop 1
	s_and_b64 vcc, vcc, s[30:31]
	s_cbranch_vccnz .Lgu_ldone
	s_add_i32 s5, s5, 1
	s_cmp_lt_u32 s5, 0x2000
	s_cbranch_scc0 .Lgu_ldone
	s_sleep 2
	global_load_dword v16, v1, s[6:7] offset:-256 sc1
	s_branch .Lgu_lpoll
.Lgu_ldone:
	s_mov_b64 s[42:43], exec
	s_mov_b64 s[30:31], exec
	s_branch .LBB0_419

; __device__ __forceinline__ unsigned xb_ld(unsigned* p)              { return __hip_atomic_load(p, __ATOMIC_RELAXED, __HIP_MEMORY_SCOPE_AGENT); }
; __device__ __forceinline__ unsigned xb_add(unsigned* p, unsigned v) { return __hip_atomic_fetch_add(p, v, __ATOMIC_RELAXED, __HIP_MEMORY_SCOPE_AGENT); }
; #define XB_SPIN(cond, bar) do { unsigned _sp = 0; while (cond) { __builtin_amdgcn_s_sleep(8); \
;     if ((++_sp & 255u) == 0u) { if (xb_ld(&(bar)[XB_TMO])) break; if (_sp > XB_SPIN_CAP) { atomicAdd(&(bar)[XB_TMO], 1u); break; } } } } while (0)
; __device__ __forceinline__ void xcd_barrier(const XcdBarrier& b) {
;     asm volatile("s_waitcnt vmcnt(0)" ::: "memory");
;     __syncthreads();
;     if (threadIdx.x == 0) {
;         unsigned* bar = b.bar;
;         __builtin_amdgcn_s_waitcnt(0);
;         unsigned nloc = b.st[0], nx = b.st[1];
;         if (nloc == 0u) { xcd_barrier_complete(bar, b.x, nloc, nx); b.st[0] = nloc; b.st[1] = nx; }
;         const unsigned old = xb_add(&bar[XB_XSUB(b.x)], 1u);
;         const unsigned gen = old / nloc;
;         if (old + 1u == (gen + 1u) * nloc) {
;             __builtin_amdgcn_fence(__ATOMIC_RELEASE, "agent");
;             asm volatile("s_waitcnt vmcnt(0)" ::: "memory");
;             const unsigned og = xb_add(&bar[XB_TOP], 1u);
;             const unsigned tg = og / nx;
;             if (og + 1u == (tg + 1u) * nx) xb_add(&bar[XB_TOPGEN], 1u);
;             else XB_SPIN(xb_ld(&bar[XB_TOPGEN]) == tg, bar);
;             __builtin_amdgcn_fence(__ATOMIC_ACQUIRE, "agent");
;             xb_add(&bar[XB_XGEN(b.x)], 1u);
;             asm volatile("s_waitcnt vmcnt(0)" ::: "memory");
;         } else {
;             XB_SPIN(xb_ld(&bar[XB_XGEN(b.x)]) == gen, bar);
;             __builtin_amdgcn_fence(__ATOMIC_ACQUIRE, "agent");
;             asm volatile("s_waitcnt vmcnt(0)" ::: "memory");
;         }
;     }
;     __syncthreads();
; }
.LBB0_502:
	v_mov_b32_e32 v14, 0x23084
	ds_read_b32 v14, v14
	v_readlane_b32 s4, v252, 23
	s_waitcnt lgkmcnt(0)
	v_readfirstlane_b32 s5, v14
	s_nop 3
	s_and_b32 s5, s4, s5
	s_cmp_eq_u32 s5, 0
	s_cbranch_scc1 .Ld_full
	v_readlane_b32 s4, v252, 34
	v_readlane_b32 s5, v252, 35
	s_and_b32 s44, s2, 7
	s_lshl_b32 s44, s44, 3
	s_bfe_u32 s45, s2, 0x30003
	s_or_b32 s44, s44, s45
	s_lshl_b32 s44, s44, 5
	s_addk_i32 s44, 0x3600
	s_add_u32 s4, s4, s44
	s_addc_u32 s5, s5, 0
	v_mov_b32_e32 v14, 0x23088
	v_mov_b32_e32 v12, 4
	ds_add_rtn_u32 v13, v14, v12
	v_mov_b32_e32 v11, 1
	s_nop 1
	global_atomic_add v1, v11, s[4:5]
	s_waitcnt lgkmcnt(0)
	v_add_u32_e32 v13, 4, v13
	s_mov_b32 s46, 0
.Ld_lpoll:
	global_load_dword v12, v1, s[4:5] sc1
	s_waitcnt vmcnt(0)
	v_cmp_ge_u32_e32 vcc, v12, v13
	s_cbranch_vccnz .Ld_ldone
	s_add_i32 s46, s46, 1
	s_cmp_lt_u32 s46, 0x2000
	s_cbranch_scc0 .Ld_ldone
	s_sleep 2
	s_branch .Ld_lpoll
.Ld_ldone:
	s_mov_b64 s[44:45], exec
	s_mov_b64 s[42:43], exec
	s_branch .LBB0_517

; __device__ __forceinline__ void xcd_barrier(const XcdBarrier& b) {
;     ...
;         if (old + 1u == (gen + 1u) * nloc) {
;             __builtin_amdgcn_fence(__ATOMIC_RELEASE, "agent");
;             asm volatile("s_waitcnt vmcnt(0)" ::: "memory");
.LBB0_518:
	s_andn2_saveexec_b64 s[4:5], s[42:43]
	s_cbranch_execz .LBB0_538
	s_mov_b64 s[42:43], exec
	v_mov_b32_e32 v15, 0x23084
	ds_read_b32 v15, v15
	s_waitcnt lgkmcnt(0)
	v_readfirstlane_b32 s5, v15
	s_nop 3
	s_cmp_lg_u32 s5, 0
	s_cbranch_scc1 .Ld1_skip_wb
	buffer_wbl2 sc1

; __device__ __forceinline__ unsigned xb_ld(unsigned* p)              { return __hip_atomic_load(p, __ATOMIC_RELAXED, __HIP_MEMORY_SCOPE_AGENT); }
; __device__ __forceinline__ unsigned xb_add(unsigned* p, unsigned v) { return __hip_atomic_fetch_add(p, v, __ATOMIC_RELAXED, __HIP_MEMORY_SCOPE_AGENT); }
; #define XB_SPIN(cond, bar) do { unsigned _sp = 0; while (cond) { __builtin_amdgcn_s_sleep(8); \
;     if ((++_sp & 255u) == 0u) { if (xb_ld(&(bar)[XB_TMO])) break; if (_sp > XB_SPIN_CAP) { atomicAdd(&(bar)[XB_TMO], 1u); break; } } } } while (0)
; __device__ __forceinline__ void xcd_barrier(const XcdBarrier& b) {
;     asm volatile("s_waitcnt vmcnt(0)" ::: "memory");
;     __syncthreads();
;     if (threadIdx.x == 0) {
;         unsigned* bar = b.bar;
;         __builtin_amdgcn_s_waitcnt(0);
;         unsigned nloc = b.st[0], nx = b.st[1];
;         if (nloc == 0u) { xcd_barrier_complete(bar, b.x, nloc, nx); b.st[0] = nloc; b.st[1] = nx; }
;         const unsigned old = xb_add(&bar[XB_XSUB(b.x)], 1u);
;         const unsigned gen = old / nloc;
;         if (old + 1u == (gen + 1u) * nloc) {
;             __builtin_amdgcn_fence(__ATOMIC_RELEASE, "agent");
;             asm volatile("s_waitcnt vmcnt(0)" ::: "memory");
;             const unsigned og = xb_add(&bar[XB_TOP], 1u);
;             const unsigned tg = og / nx;
;             if (og + 1u == (tg + 1u) * nx) xb_add(&bar[XB_TOPGEN], 1u);
;             else XB_SPIN(xb_ld(&bar[XB_TOPGEN]) == tg, bar);
;             __builtin_amdgcn_fence(__ATOMIC_ACQUIRE, "agent");
;             xb_add(&bar[XB_XGEN(b.x)], 1u);
;             asm volatile("s_waitcnt vmcnt(0)" ::: "memory");
;         } else {
;             XB_SPIN(xb_ld(&bar[XB_XGEN(b.x)]) == gen, bar);
;             __builtin_amdgcn_fence(__ATOMIC_ACQUIRE, "agent");
;             asm volatile("s_waitcnt vmcnt(0)" ::: "memory");
;         }
;     }
;     __syncthreads();
; }
.LBB0_1241:
	v_mov_b32_e32 v14, 0x23084
	ds_read_b32 v14, v14
	s_waitcnt lgkmcnt(0)
	v_readfirstlane_b32 s5, v14
	s_nop 3
	s_cmp_eq_u32 s5, 0
	s_cbranch_scc1 .Lout_full
	v_readlane_b32 s4, v252, 34
	v_readlane_b32 s5, v252, 35
	s_and_b32 s6, s2, 7
	s_lshl_b32 s6, s6, 3
	s_bfe_u32 s7, s2, 0x30003
	s_or_b32 s6, s6, s7
	s_lshl_b32 s6, s6, 5
	s_addk_i32 s6, 0x3600
	s_add_u32 s4, s4, s6
	s_addc_u32 s5, s5, 0
	v_mov_b32_e32 v14, 0x23088
	v_mov_b32_e32 v12, 4
	ds_add_rtn_u32 v13, v14, v12
	v_mov_b32_e32 v11, 1
	s_nop 1
	global_atomic_add v1, v11, s[4:5]
	s_waitcnt lgkmcnt(0)
	v_add_u32_e32 v13, 4, v13
	s_mov_b32 s8, 0
.Lout_lpoll:
	global_load_dword v12, v1, s[4:5] sc1
	s_waitcnt vmcnt(0)
	v_cmp_ge_u32_e32 vcc, v12, v13
	s_cbranch_vccnz .Lout_ldone
	s_add_i32 s8, s8, 1
	s_cmp_lt_u32 s8, 0x2000
	s_cbranch_scc0 .Lout_ldone
	s_sleep 2
	s_branch .Lout_lpoll
